# comb1 + layer-1 attention P.V block with 8-deep pipelined V-fragment reads and v_max3 row max
# speedup vs baseline: 1.0067x; 1.0067x over previous
; #define LAS __attribute__((address_space(3)))
; __device__ __forceinline__ unsigned cvt_pk(float lo, float hi) { unsigned r; asm volatile("v_cvt_pk_bf16_f32 %0, %1, %2" : "=v"(r) : "v"(lo), "v"(hi)); return r; }
; __device__ __forceinline__ void attn_unit(LAS unsigned char* lds, int b, int h, int q0, int kbeg, int ntiles, const bf16_t* Q, const bf16_t* K, const bf16_t* Vt, bf16_t* cat) {
;     ...
;         const LAS unsigned char* kb = lds + (buf ^ 1) * AK_BYTES + r32 * (KP * 2) + hi * 16;
;         f32x16 pn0, pn1;
; #pragma unroll
;         for (int r = 0; r < 16; ++r) { pn0[r] = 0.f; pn1[r] = 0.f; }
;         float ps = 0.f; u32x4 pw[4];
;         bf16x8 ka = *(const LAS bf16x8*)(kb), kbb = *(const LAS bf16x8*)(kb + 32 * (KP * 2));
; #pragma unroll
;         for (int ds = 0; ds < 12; ++ds) {
;             bf16x8 na = ka, nb = kbb;
;             if (ds < 11) { na = *(const LAS bf16x8*)(kb + (ds + 1) * 32); nb = *(const LAS bf16x8*)(kb + 32 * (KP * 2) + (ds + 1) * 32); }
;             pn0 = __builtin_amdgcn_mfma_f32_32x32x16_bf16(ka, qf[ds], pn0, 0, 0, 0);
;             pn1 = __builtin_amdgcn_mfma_f32_32x32x16_bf16(kbb, qf[ds], pn1, 0, 0, 0);
;             if (ds < 8) {
;                 float e[4];
; #pragma unroll
;                 for (int j = 0; j < 4; ++j) { const float v = ds < 4 ? pc0[4 * ds + j] : pc1[4 * (ds - 4) + j]; e[j] = __builtin_amdgcn_exp2f(v - mrun); }
;                 ps += (e[0] + e[1]) + (e[2] + e[3]);
;                 const unsigned w0 = cvt_pk(e[0], e[1]), w1 = cvt_pk(e[2], e[3]);
;                 if ((ds & 1) == 0) { pw[ds >> 1].x = w0; pw[ds >> 1].y = w1; } else { pw[ds >> 1].z = w0; pw[ds >> 1].w = w1; }
;             }
;             ka = na; kbb = nb;
;             __builtin_amdgcn_sched_barrier(0);
;         }
.LBB0_1840:
	s_xor_b32 s6, s5, 1
	s_mul_i32 s7, s6, 0x6400
	v_add_u32_e32 v233, s7, v229
	ds_read_b128 v[98:101], v233
	v_sub_f32_e32 v82, v82, v231
	v_exp_f32_e32 v197, v82
	v_sub_f32_e32 v82, v84, v231
	v_exp_f32_e32 v201, v82
	v_sub_f32_e32 v82, v85, v231
	v_exp_f32_e32 v235, v82
	v_sub_f32_e32 v82, v86, v231
	v_exp_f32_e32 v196, v82
	v_sub_f32_e32 v82, v87, v231
	s_waitcnt lgkmcnt(0)
	v_mfma_f32_32x32x16_bf16 v[98:113], v[98:101], v[174:177], 0
	v_exp_f32_e32 v198, v82
	v_sub_f32_e32 v82, v88, v231
	v_sub_f32_e32 v83, v83, v231
	v_exp_f32_e32 v200, v82
	v_sub_f32_e32 v82, v89, v231
	v_exp_f32_e32 v199, v83
	v_exp_f32_e32 v234, v82
	ds_read_b128 v[188:191], v233 offset:32
	ds_read_b128 v[114:117], v233 offset:12800
	ds_read_b128 v[192:195], v233 offset:12832
	s_add_i32 s4, s4, 1
	v_pk_add_f32 v[82:83], v[196:197], v[198:199]
	v_pk_add_f32 v[84:85], v[200:201], v[234:235]
	s_waitcnt lgkmcnt(0)
	v_mfma_f32_32x32x16_bf16 v[114:129], v[114:117], v[174:177], 0
	v_add_f32_e64 v236, v82, v84
	v_add_f32_e64 v237, v83, v85
	v_cvt_pk_bf16_f32 v186, v197, v199
	v_cvt_pk_bf16_f32 v187, v201, v235
	v_add_f32_e32 v237, 0, v237
	v_mfma_f32_32x32x16_bf16 v[98:113], v[188:191], v[170:173], v[98:113]
	ds_read_b128 v[82:85], v233 offset:64
	ds_read_b128 v[86:89], v233 offset:12864
	v_add_f32_e32 v197, v236, v237
	v_cvt_pk_bf16_f32 v188, v196, v198
	v_cvt_pk_bf16_f32 v189, v200, v234
	v_mfma_f32_32x32x16_bf16 v[114:129], v[192:195], v[170:173], v[114:129]
	v_sub_f32_e32 v90, v90, v231
	s_waitcnt lgkmcnt(0)
	v_mfma_f32_32x32x16_bf16 v[98:113], v[82:85], v[166:169], v[98:113]
	v_exp_f32_e32 v190, v90
	v_sub_f32_e32 v90, v91, v231
	v_exp_f32_e32 v192, v90
	v_sub_f32_e32 v90, v92, v231
	v_sub_f32_e32 v82, v93, v231
	v_exp_f32_e32 v191, v90
	v_exp_f32_e32 v193, v82
	ds_read_b128 v[82:85], v233 offset:96
	ds_read_b128 v[90:93], v233 offset:12896
	v_mfma_f32_32x32x16_bf16 v[114:129], v[86:89], v[166:169], v[114:129]
	v_add_f32_e64 v194, v190, v192
	v_add_f32_e64 v195, v191, v193
	v_add_f32_e64 v198, v194, v194
	v_add_f32_e64 v199, v194, v195
	v_cvt_pk_bf16_f32 v190, v190, v192
	v_cvt_pk_bf16_f32 v191, v191, v193
	v_sub_f32_e32 v86, v94, v231
	s_waitcnt lgkmcnt(0)
	v_mfma_f32_32x32x16_bf16 v[98:113], v[82:85], v[162:165], v[98:113]
	v_exp_f32_e32 v94, v86
	v_sub_f32_e32 v86, v95, v231
	v_exp_f32_e32 v192, v86
	v_sub_f32_e32 v86, v96, v231
	v_sub_f32_e32 v82, v97, v231
	v_exp_f32_e32 v96, v86
	v_exp_f32_e32 v193, v82
	ds_read_b128 v[82:85], v233 offset:128
	ds_read_b128 v[86:89], v233 offset:12928
	v_add_f32_e32 v95, v94, v192
	v_cvt_pk_bf16_f32 v192, v94, v192
	v_add_f32_e32 v97, v96, v193
	v_mfma_f32_32x32x16_bf16 v[114:129], v[90:93], v[162:165], v[114:129]
	v_cvt_pk_bf16_f32 v193, v96, v193
	v_sub_f32_e32 v66, v66, v231
	v_exp_f32_e32 v94, v66
	v_sub_f32_e32 v66, v67, v231
	v_exp_f32_e32 v96, v66
	v_sub_f32_e32 v66, v68, v231
	v_exp_f32_e32 v198, v66
	s_waitcnt lgkmcnt(0)
	v_mfma_f32_32x32x16_bf16 v[98:113], v[82:85], v[158:161], v[98:113]
	v_sub_f32_e32 v66, v69, v231
	v_exp_f32_e32 v196, v66
	ds_read_b128 v[66:69], v233 offset:160
	ds_read_b128 v[82:85], v233 offset:12960
	v_pk_add_f32 v[90:91], v[94:95], v[96:97]
	v_cvt_pk_bf16_f32 v194, v94, v96
	v_pk_add_f32 v[92:93], v[198:199], v[196:197]
	v_cvt_pk_bf16_f32 v195, v198, v196
	v_mfma_f32_32x32x16_bf16 v[114:129], v[86:89], v[158:161], v[114:129]
	v_add_f32_e64 v90, v90, v92
	v_add_f32_e64 v91, v91, v93
	v_add_f32_e64 v86, v90, v90
	v_add_f32_e64 v87, v90, v91
	v_sub_f32_e32 v70, v70, v231
	v_exp_f32_e32 v88, v70
	v_sub_f32_e32 v70, v71, v231
	s_waitcnt lgkmcnt(0)
	v_mfma_f32_32x32x16_bf16 v[98:113], v[66:69], v[154:157], v[98:113]
	v_exp_f32_e32 v90, v70
	v_sub_f32_e32 v70, v72, v231
	v_sub_f32_e32 v66, v73, v231
	v_exp_f32_e32 v89, v70
	v_exp_f32_e32 v91, v66
	ds_read_b128 v[66:69], v233 offset:192
	ds_read_b128 v[70:73], v233 offset:12992
	v_cvt_pk_bf16_f32 v196, v88, v90
	v_mfma_f32_32x32x16_bf16 v[114:129], v[82:85], v[154:157], v[114:129]
	v_add_f32_e64 v92, v88, v90
	v_add_f32_e64 v93, v89, v91
	v_cvt_pk_bf16_f32 v197, v89, v91
	v_pk_add_f32 v[92:93], v[92:93], v[92:93] op_sel_hi:[0,1]
	v_sub_f32_e32 v74, v74, v231
	s_waitcnt lgkmcnt(0)
	v_mfma_f32_32x32x16_bf16 v[98:113], v[66:69], v[150:153], v[98:113]
	v_exp_f32_e32 v82, v74
	v_sub_f32_e32 v74, v75, v231
	v_exp_f32_e32 v84, v74
	v_sub_f32_e32 v74, v76, v231
	v_sub_f32_e32 v66, v77, v231
	v_exp_f32_e32 v86, v74
	v_exp_f32_e32 v88, v66
	ds_read_b128 v[66:69], v233 offset:224
	ds_read_b128 v[74:77], v233 offset:13024
	v_add_f32_e32 v83, v82, v84
	v_cvt_pk_bf16_f32 v198, v82, v84
	v_add_f32_e32 v85, v86, v88
	v_mfma_f32_32x32x16_bf16 v[114:129], v[70:73], v[150:153], v[114:129]
	v_cvt_pk_bf16_f32 v199, v86, v88
	v_sub_f32_e32 v70, v78, v231
	v_exp_f32_e32 v82, v70
	v_sub_f32_e32 v70, v79, v231
	s_waitcnt lgkmcnt(0)
; #define LAS __attribute__((address_space(3)))
; #define ASTOREV(buf) do { LAS unsigned char* vd_ = lds + 2 * AK_BYTES + (buf) * AV_BYTES + vd0 * AV_PITCH + vpart * 16; \
;         *(LAS u32x2*)(vd_) = (u32x2){vr[0].x, vr[0].y}; *(LAS u32x2*)(vd_ + 8) = (u32x2){vr[0].z, vr[0].w}; \
;         *(LAS u32x2*)(vd_ + 64 * AV_PITCH) = (u32x2){vr[1].x, vr[1].y}; *(LAS u32x2*)(vd_ + 64 * AV_PITCH + 8) = (u32x2){vr[1].z, vr[1].w}; } while (0)
; __device__ __forceinline__ void attn_unit(LAS unsigned char* lds, int b, int h, int q0, int kbeg, int ntiles, const bf16_t* Q, const bf16_t* K, const bf16_t* Vt, bf16_t* cat) {
;     ...
;         lrun += ps;
;         const LAS unsigned char* vb = lds + 2 * AK_BYTES + buf * AV_BYTES + r32 * AV_PITCH + hi * 8;
; #pragma unroll
;         for (int d = 0; d < 4; ++d)
; #pragma unroll
;             for (int ks = 0; ks < 4; ++ks) {
;                 const s16x4 lo = *(const LAS s16x4*)(vb + d * 32 * AV_PITCH + ks * 32), hh = *(const LAS s16x4*)(vb + d * 32 * AV_PITCH + ks * 32 + 16);
;                 const bf16x8 vf = (bf16x8){lo[0], lo[1], lo[2], lo[3], hh[0], hh[1], hh[2], hh[3]};
;                 o[d] = __builtin_amdgcn_mfma_f32_32x32x16_bf16(vf, __builtin_bit_cast(bf16x8, pw[ks]), o[d], 0, 0, 0);
;             }
;         { float mx = fmaxf(pn0[0], pn1[0]);
; #pragma unroll
;           for (int r = 1; r < 16; ++r) mx = fmaxf(mx, fmaxf(pn0[r], pn1[r]));
;           mxc = fmaxf(mx, __shfl_xor(mx, 32)); }
;         if (kt + 1 < ntiles) ASTOREV(buf ^ 1);
;         asm volatile("s_waitcnt vmcnt(0)" ::: "memory");
;         __syncthreads();
;         pc0 = pn0; pc1 = pn1;
	v_mfma_f32_32x32x16_bf16 v[98:113], v[66:69], v[146:149], v[98:113]
	v_exp_f32_e32 v84, v70
	v_sub_f32_e32 v70, v80, v231
	v_sub_f32_e32 v66, v81, v231
	v_exp_f32_e32 v92, v70
	v_exp_f32_e32 v86, v66
	ds_read_b128 v[66:69], v233 offset:256
	ds_read_b128 v[70:73], v233 offset:13056
	v_pk_add_f32 v[78:79], v[82:83], v[84:85]
	v_mfma_f32_32x32x16_bf16 v[114:129], v[74:77], v[146:149], v[114:129]
	v_add_f32_e64 v80, v92, v86
	v_add_f32_e64 v81, v93, v87
	v_cvt_pk_bf16_f32 v200, v82, v84
	v_cvt_pk_bf16_f32 v201, v92, v86
	v_add_f32_e64 v78, v78, v80
	v_add_f32_e64 v79, v79, v81
	v_add_f32_e32 v238, v78, v79
	s_waitcnt lgkmcnt(0)
	v_mfma_f32_32x32x16_bf16 v[98:113], v[66:69], v[142:145], v[98:113]
	ds_read_b128 v[66:69], v233 offset:288
	ds_read_b128 v[74:77], v233 offset:13088
	v_mfma_f32_32x32x16_bf16 v[114:129], v[70:73], v[142:145], v[114:129]
	s_waitcnt lgkmcnt(0)
	v_mfma_f32_32x32x16_bf16 v[98:113], v[66:69], v[138:141], v[98:113]
	ds_read_b128 v[66:69], v233 offset:320
	ds_read_b128 v[70:73], v233 offset:13120
	v_mfma_f32_32x32x16_bf16 v[114:129], v[74:77], v[138:141], v[114:129]
	s_waitcnt lgkmcnt(0)
	v_mfma_f32_32x32x16_bf16 v[98:113], v[66:69], v[134:137], v[98:113]
	ds_read_b128 v[66:69], v233 offset:352
	ds_read_b128 v[234:237], v233 offset:13152
	v_mfma_f32_32x32x16_bf16 v[114:129], v[70:73], v[134:137], v[114:129]
	s_waitcnt lgkmcnt(0)
	v_mfma_f32_32x32x16_bf16 v[82:97], v[66:69], v[130:133], v[98:113]
	v_mfma_f32_32x32x16_bf16 v[66:81], v[234:237], v[130:133], v[114:129]
	s_mulk_i32 s5, 0x4400
	v_add_u32_e32 v233, s5, v230
	v_add_u32_e32 v250, 0xc800, v233
	v_add_u32_e32 v251, 0xd800, v233
	v_add_u32_e32 v252, 0xe800, v233
	v_add_u32_e32 v253, 0xf800, v233
	s_mulk_i32 s6, 0x4400
	ds_read2_b64 v[98:101], v250 offset1:2
	ds_read2_b64 v[102:105], v251 offset0:32 offset1:34
	ds_read2_b64 v[106:109], v252 offset0:64 offset1:66
	ds_read2_b64 v[110:113], v253 offset0:96 offset1:98
	ds_read2_b64 v[114:117], v250 offset0:4 offset1:6
	ds_read2_b64 v[118:121], v251 offset0:36 offset1:38
	ds_read2_b64 v[122:125], v252 offset0:68 offset1:70
	ds_read2_b64 v[126:129], v253 offset0:100 offset1:102
	v_add_f32_e32 v202, v202, v238
	v_max3_f32 v254, v82, v66, v83
	v_max3_f32 v254, v254, v67, v84
	v_max3_f32 v254, v254, v68, v85
	v_max3_f32 v254, v254, v69, v86
	s_waitcnt lgkmcnt(7)
	v_mfma_f32_32x32x16_bf16 v[50:65], v[98:101], v[186:189], v[50:65]
	ds_read2_b64 v[98:101], v250 offset0:8 offset1:10
	v_max3_f32 v254, v254, v70, v87
	v_max3_f32 v254, v254, v71, v88
	s_waitcnt lgkmcnt(7)
	v_mfma_f32_32x32x16_bf16 v[34:49], v[102:105], v[186:189], v[34:49]
	ds_read2_b64 v[102:105], v251 offset0:40 offset1:42
	v_max3_f32 v254, v254, v72, v89
	v_max3_f32 v254, v254, v73, v90
	s_waitcnt lgkmcnt(7)
	v_mfma_f32_32x32x16_bf16 v[18:33], v[106:109], v[186:189], v[18:33]
	ds_read2_b64 v[106:109], v252 offset0:72 offset1:74
	v_max3_f32 v254, v254, v74, v91
	v_max3_f32 v254, v254, v75, v92
	s_waitcnt lgkmcnt(7)
	v_mfma_f32_32x32x16_bf16 v[2:17], v[110:113], v[186:189], v[2:17]
	ds_read2_b64 v[110:113], v253 offset0:104 offset1:106
	v_max3_f32 v254, v254, v76, v93
	v_max3_f32 v254, v254, v77, v94
	s_waitcnt lgkmcnt(7)
	v_mfma_f32_32x32x16_bf16 v[50:65], v[114:117], v[190:193], v[50:65]
	ds_read2_b64 v[114:117], v250 offset0:12 offset1:14
	v_max3_f32 v254, v254, v78, v95
	v_max3_f32 v254, v254, v79, v96
	s_waitcnt lgkmcnt(7)
	v_mfma_f32_32x32x16_bf16 v[34:49], v[118:121], v[190:193], v[34:49]
	ds_read2_b64 v[118:121], v251 offset0:44 offset1:46
	v_max3_f32 v254, v254, v80, v97
	v_max_f32_e32 v254, v254, v81
	s_waitcnt lgkmcnt(7)
	v_mfma_f32_32x32x16_bf16 v[18:33], v[122:125], v[190:193], v[18:33]
	ds_read2_b64 v[122:125], v252 offset0:76 offset1:78
	v_lshl_add_u64 v[214:215], v[214:215], 0, s[38:39]
	v_lshl_add_u64 v[216:217], v[216:217], 0, s[38:39]
	s_waitcnt lgkmcnt(7)
	v_mfma_f32_32x32x16_bf16 v[2:17], v[126:129], v[190:193], v[2:17]
	ds_read2_b64 v[126:129], v253 offset0:108 offset1:110
	v_lshl_add_u64 v[218:219], v[218:219], 0, s[38:39]
	v_lshl_add_u64 v[220:221], v[220:221], 0, s[38:39]
	v_lshl_add_u64 v[222:223], v[222:223], 0, s[40:41]
	ds_bpermute_b32 v255, v209, v254
	s_waitcnt lgkmcnt(8)
	v_mfma_f32_32x32x16_bf16 v[50:65], v[98:101], v[194:197], v[50:65]
	s_waitcnt lgkmcnt(7)
	v_mfma_f32_32x32x16_bf16 v[34:49], v[102:105], v[194:197], v[34:49]
	s_waitcnt lgkmcnt(6)
	v_mfma_f32_32x32x16_bf16 v[18:33], v[106:109], v[194:197], v[18:33]
	s_waitcnt lgkmcnt(5)
	v_mfma_f32_32x32x16_bf16 v[2:17], v[110:113], v[194:197], v[2:17]
	s_waitcnt lgkmcnt(0)
	v_max_f32_e32 v255, v255, v255
	v_max_f32_e32 v98, v254, v255
	v_add_u32_e32 v255, s6, v232
	v_add_u32_e32 v239, 0xc800, v255
	v_add_u32_e32 v255, 0xea00, v255
	s_cmp_lg_u32 s4, 34
	s_waitcnt vmcnt(0)
	ds_write2_b64 v239, v[178:179], v[180:181] offset1:1
	ds_write2_b64 v255, v[182:183], v[184:185] offset1:1
	s_waitcnt vmcnt(0)
	s_waitcnt lgkmcnt(0)
	s_barrier
	v_mfma_f32_32x32x16_bf16 v[50:65], v[114:117], v[198:201], v[50:65]
	v_mfma_f32_32x32x16_bf16 v[34:49], v[118:121], v[198:201], v[34:49]
	v_mfma_f32_32x32x16_bf16 v[18:33], v[122:125], v[198:201], v[18:33]
	v_mfma_f32_32x32x16_bf16 v[2:17], v[126:129], v[198:201], v[2:17]
	s_cbranch_scc0 .LBB0_1845

; __global__ void __launch_bounds__(512, 2) mk_fwd(Args args) {
	.amdhsa_kernel _Z6mk_fwd4Args
		.amdhsa_group_segment_fixed_size 0
		.amdhsa_private_segment_fixed_size 0
		.amdhsa_kernarg_size 440
		.amdhsa_user_sgpr_count 2
		.amdhsa_user_sgpr_dispatch_ptr 0
		.amdhsa_user_sgpr_queue_ptr 0
		.amdhsa_user_sgpr_kernarg_segment_ptr 1
		.amdhsa_user_sgpr_dispatch_id 0
		.amdhsa_user_sgpr_kernarg_preload_length 0
		.amdhsa_user_sgpr_kernarg_preload_offset 0
		.amdhsa_user_sgpr_private_segment_size 0
		.amdhsa_uses_dynamic_stack 0
		.amdhsa_enable_private_segment 0
		.amdhsa_system_sgpr_workgroup_id_x 1
		.amdhsa_system_sgpr_workgroup_id_y 0
		.amdhsa_system_sgpr_workgroup_id_z 0
		.amdhsa_system_sgpr_workgroup_info 0
		.amdhsa_system_vgpr_workitem_id 2
		.amdhsa_next_free_vgpr 256
		.amdhsa_next_free_sgpr 98
		.amdhsa_accum_offset 256
		.amdhsa_reserve_vcc 1
		.amdhsa_float_round_mode_32 0
		.amdhsa_float_round_mode_16_64 0
		.amdhsa_float_denorm_mode_32 3
		.amdhsa_float_denorm_mode_16_64 3
		.amdhsa_dx10_clamp 1
		.amdhsa_ieee_mode 1
		.amdhsa_fp16_overflow 0
		.amdhsa_tg_split 0
		.amdhsa_exception_fp_ieee_invalid_op 0
		.amdhsa_exception_fp_denorm_src 0
		.amdhsa_exception_fp_ieee_div_zero 0
		.amdhsa_exception_fp_ieee_overflow 0
		.amdhsa_exception_fp_ieee_underflow 0
		.amdhsa_exception_fp_ieee_inexact 0
		.amdhsa_exception_int_div_zero 0
	.end_amdhsa_kernel

; __global__ void __launch_bounds__(512, 2) mk_fwd(Args args) {
amdhsa.kernels:
  - .agpr_count:     0
    .args:
      - .offset:         0
        .size:           184
        .value_kind:     by_value
      - .offset:         184
        .size:           4
        .value_kind:     hidden_block_count_x
      - .offset:         188
        .size:           4
        .value_kind:     hidden_block_count_y
      - .offset:         192
        .size:           4
        .value_kind:     hidden_block_count_z
      - .offset:         196
        .size:           2
        .value_kind:     hidden_group_size_x
      - .offset:         198
        .size:           2
        .value_kind:     hidden_group_size_y
      - .offset:         200
        .size:           2
        .value_kind:     hidden_group_size_z
      - .offset:         202
        .size:           2
        .value_kind:     hidden_remainder_x
      - .offset:         204
        .size:           2
        .value_kind:     hidden_remainder_y
      - .offset:         206
        .size:           2
        .value_kind:     hidden_remainder_z
      - .offset:         224
        .size:           8
        .value_kind:     hidden_global_offset_x
      - .offset:         232
        .size:           8
        .value_kind:     hidden_global_offset_y
      - .offset:         240
        .size:           8
        .value_kind:     hidden_global_offset_z
      - .offset:         248
        .size:           2
        .value_kind:     hidden_grid_dims
      - .offset:         272
        .size:           8
        .value_kind:     hidden_multigrid_sync_arg
      - .offset:         304
        .size:           4
        .value_kind:     hidden_dynamic_lds_size
    .group_segment_fixed_size: 0
    .kernarg_segment_align: 8
    .kernarg_segment_size: 440
    .language:       OpenCL C
    .language_version:
      - 2
      - 0
    .max_flat_workgroup_size: 512
    .name:           _Z6mk_fwd4Args
    .private_segment_fixed_size: 0
    .sgpr_count:     104
    .sgpr_spill_count: 19
    .symbol:         _Z6mk_fwd4Args.kd
    .uniform_work_group_size: 1
    .uses_dynamic_stack: false
    .vgpr_count:     256
    .vgpr_spill_count: 0
    .wavefront_size: 64
